# copy engines stop grabbing when all but 64 workers (phase engines) / 128 of 192 busy workers (tail engines) have arrived, so their last grab overlaps the stragglers
# speedup vs baseline: 1.0152x; 1.0152x over previous
.LBB0_184:
	v_mov_b32_e32 v31, -1
	s_mov_b64 s[0:1], exec
	v_readlane_b32 s2, v242, 26
	v_readlane_b32 s3, v242, 27
	s_and_b64 s[2:3], s[0:1], s[2:3]
	s_mov_b64 exec, s[2:3]
	s_cbranch_execz .LBB0_189
	v_readlane_b32 s2, v241, 2
	v_readlane_b32 s3, v241, 3
	v_mov_b32_e32 v31, -1
	s_nop 3
	global_load_dword v2, v1, s[2:3] sc1
	v_readlane_b32 s2, v241, 4
	v_readlane_b32 s3, v241, 5
	s_nop 4
	global_load_dword v3, v1, s[2:3] sc1
	v_readlane_b32 s2, v241, 6
	v_readlane_b32 s3, v241, 7
	s_nop 4
	global_load_dword v4, v1, s[2:3] sc1
	v_readlane_b32 s2, v241, 8
	v_readlane_b32 s3, v241, 9
	s_nop 4
	global_load_dword v5, v1, s[2:3] sc1
	v_readlane_b32 s2, v241, 10
	v_readlane_b32 s3, v241, 11
	s_nop 4
	global_load_dword v6, v1, s[2:3] sc1
	v_readlane_b32 s2, v241, 12
	v_readlane_b32 s3, v241, 13
	s_nop 4
	global_load_dword v7, v1, s[2:3] sc1
	global_load_dword v8, v1, s[34:35] sc1
	global_load_dword v9, v1, s[40:41] sc1
	global_load_dword v10, v1, s[42:43] sc1
	global_load_dword v11, v1, s[50:51] sc1
	global_load_dword v12, v1, s[56:57] sc1
	global_load_dword v13, v1, s[60:61] sc1
	global_load_dword v14, v1, s[62:63] sc1
	global_load_dword v15, v1, s[64:65] sc1
	global_load_dword v16, v1, s[68:69] sc1
	global_load_dword v17, v1, s[70:71] sc1
	v_readlane_b32 s2, v242, 25
	s_mul_i32 s2, s84, s2
	s_waitcnt vmcnt(15)
	v_subrev_u32_e32 v2, s2, v2
	s_waitcnt vmcnt(14)
	v_add_u32_e32 v2, v2, v3
	s_waitcnt vmcnt(13)
	v_add_u32_e32 v2, v2, v4
	s_waitcnt vmcnt(12)
	v_add_u32_e32 v2, v2, v5
	s_waitcnt vmcnt(11)
	v_add_u32_e32 v2, v2, v6
	s_waitcnt vmcnt(10)
	v_add_u32_e32 v2, v2, v7
	s_waitcnt vmcnt(9)
	v_add_u32_e32 v2, v2, v8
	s_waitcnt vmcnt(8)
	v_add_u32_e32 v2, v2, v9
	s_waitcnt vmcnt(7)
	v_add_u32_e32 v2, v2, v10
	s_waitcnt vmcnt(6)
	v_add_u32_e32 v2, v2, v11
	s_waitcnt vmcnt(5)
	v_add_u32_e32 v2, v2, v12
	s_waitcnt vmcnt(4)
	v_add_u32_e32 v2, v2, v13
	s_waitcnt vmcnt(3)
	v_add_u32_e32 v2, v2, v14
	s_waitcnt vmcnt(2)
	v_add_u32_e32 v2, v2, v15
	s_waitcnt vmcnt(1)
	v_add_u32_e32 v2, v2, v16
	s_waitcnt vmcnt(0)
	v_add_u32_e32 v2, v2, v17
	v_add_u32_e32 v2, 64, v2
	v_cmp_le_u32_e32 vcc, s33, v2
	s_cbranch_vccnz .LBB0_189
	s_mov_b64 s[6:7], exec
	v_mbcnt_lo_u32_b32 v2, s6, 0
	v_mbcnt_hi_u32_b32 v2, s7, v2
	v_cmp_eq_u32_e32 vcc, 0, v2
	s_and_saveexec_b64 s[2:3], vcc
	s_cbranch_execz .LBB0_188
	s_bcnt1_i32_b64 s4, s[6:7]
	s_lshl_b32 s4, s4, 3
	v_readlane_b32 s6, v242, 43
	v_mov_b32_e32 v3, s4
	v_readlane_b32 s7, v242, 44
	s_nop 4
	global_atomic_add v3, v1, v3, s[6:7] sc0

.LBB0_527:
	v_mov_b32_e32 v31, -1
	s_mov_b64 s[0:1], exec
	v_readlane_b32 s2, v242, 26
	v_readlane_b32 s3, v242, 27
	s_and_b64 s[2:3], s[0:1], s[2:3]
	s_mov_b64 exec, s[2:3]
	s_cbranch_execz .LBB0_532
	v_readlane_b32 s2, v241, 2
	v_readlane_b32 s3, v241, 3
	v_mov_b32_e32 v31, -1
	s_nop 3
	global_load_dword v2, v1, s[2:3] sc1
	v_readlane_b32 s2, v241, 4
	v_readlane_b32 s3, v241, 5
	s_waitcnt vmcnt(0)
	v_subrev_u32_e32 v2, s55, v2
	s_nop 2
	global_load_dword v3, v1, s[2:3] sc1
	v_readlane_b32 s2, v241, 6
	v_readlane_b32 s3, v241, 7
	s_waitcnt vmcnt(0)
	v_add_u32_e32 v2, v2, v3
	s_nop 2
	global_load_dword v4, v1, s[2:3] sc1
	v_readlane_b32 s2, v241, 8
	v_readlane_b32 s3, v241, 9
	s_waitcnt vmcnt(0)
	v_add_u32_e32 v2, v2, v4
	s_nop 2
	global_load_dword v5, v1, s[2:3] sc1
	v_readlane_b32 s2, v241, 10
	v_readlane_b32 s3, v241, 11
	s_waitcnt vmcnt(0)
	v_add_u32_e32 v2, v2, v5
	s_nop 2
	global_load_dword v6, v1, s[2:3] sc1
	v_readlane_b32 s2, v241, 12
	v_readlane_b32 s3, v241, 13
	s_nop 4
	global_load_dword v7, v1, s[2:3] sc1
	global_load_dword v8, v1, s[34:35] sc1
	global_load_dword v9, v1, s[40:41] sc1
	global_load_dword v10, v1, s[42:43] sc1
	global_load_dword v11, v1, s[50:51] sc1
	global_load_dword v12, v1, s[56:57] sc1
	global_load_dword v13, v1, s[60:61] sc1
	global_load_dword v14, v1, s[62:63] sc1
	global_load_dword v15, v1, s[64:65] sc1
	global_load_dword v16, v1, s[68:69] sc1
	global_load_dword v17, v1, s[70:71] sc1
	s_movk_i32 s2, 0x7f
	s_waitcnt vmcnt(11)
	v_add_u32_e32 v2, v2, v6
	s_waitcnt vmcnt(10)
	v_add_u32_e32 v2, v2, v7
	s_waitcnt vmcnt(9)
	v_add_u32_e32 v2, v2, v8
	s_waitcnt vmcnt(8)
	v_add_u32_e32 v2, v2, v9
	s_waitcnt vmcnt(7)
	v_add_u32_e32 v2, v2, v10
	s_waitcnt vmcnt(6)
	v_add_u32_e32 v2, v2, v11
	s_waitcnt vmcnt(5)
	v_add_u32_e32 v2, v2, v12
	s_waitcnt vmcnt(4)
	v_add_u32_e32 v2, v2, v13
	s_waitcnt vmcnt(3)
	v_add_u32_e32 v2, v2, v14
	s_waitcnt vmcnt(2)
	v_add_u32_e32 v2, v2, v15
	s_waitcnt vmcnt(1)
	v_add_u32_e32 v2, v2, v16
	s_waitcnt vmcnt(0)
	v_add_u32_e32 v2, v2, v17
	v_cmp_lt_u32_e32 vcc, s2, v2
	s_cbranch_vccnz .LBB0_532
	s_mov_b64 s[6:7], exec
	v_mbcnt_lo_u32_b32 v2, s6, 0
	v_mbcnt_hi_u32_b32 v2, s7, v2
	v_cmp_eq_u32_e32 vcc, 0, v2
	s_and_saveexec_b64 s[2:3], vcc
	s_cbranch_execz .LBB0_531
	s_bcnt1_i32_b64 s4, s[6:7]
	s_lshl_b32 s4, s4, 3
	v_readlane_b32 s6, v242, 43
	v_mov_b32_e32 v3, s4
	v_readlane_b32 s7, v242, 44
	s_nop 4
	global_atomic_add v3, v1, v3, s[6:7] sc0

.LBB0_1761:
	v_mov_b32_e32 v31, -1
	s_mov_b64 s[48:49], exec
	v_readlane_b32 s0, v242, 26
	v_readlane_b32 s1, v242, 27
	s_and_b64 s[0:1], s[48:49], s[0:1]
	s_mov_b64 exec, s[0:1]
	s_cbranch_execz .LBB0_1766
	v_readlane_b32 s0, v242, 30
	v_readlane_b32 s1, v242, 31
	v_mov_b32_e32 v31, -1
	s_nop 3
	global_load_dword v2, v1, s[0:1] sc1
	v_readlane_b32 s0, v241, 2
	v_readlane_b32 s1, v241, 3
	s_nop 4
	global_load_dword v3, v1, s[0:1] sc1
	v_readlane_b32 s0, v241, 4
	v_readlane_b32 s1, v241, 5
	s_nop 4
	global_load_dword v4, v1, s[0:1] sc1
	v_readlane_b32 s0, v241, 6
	v_readlane_b32 s1, v241, 7
	s_nop 4
	global_load_dword v5, v1, s[0:1] sc1
	v_readlane_b32 s0, v241, 8
	v_readlane_b32 s1, v241, 9
	s_nop 4
	global_load_dword v6, v1, s[0:1] sc1
	global_load_dword v7, v1, s[14:15] sc1
	global_load_dword v8, v1, s[16:17] sc1
	global_load_dword v9, v1, s[18:19] sc1
	global_load_dword v10, v1, s[20:21] sc1
	global_load_dword v11, v1, s[22:23] sc1
	global_load_dword v12, v1, s[24:25] sc1
	global_load_dword v13, v1, s[26:27] sc1
	global_load_dword v14, v1, s[28:29] sc1
	global_load_dword v15, v1, s[30:31] sc1
	global_load_dword v16, v1, s[34:35] sc1
	global_load_dword v17, v1, s[40:41] sc1
	v_readlane_b32 s0, v242, 25
	s_mul_i32 s0, s84, s0
	s_waitcnt vmcnt(15)
	v_subrev_u32_e32 v2, s0, v2
	s_waitcnt vmcnt(14)
	v_add_u32_e32 v2, v2, v3
	s_waitcnt vmcnt(13)
	v_add_u32_e32 v2, v2, v4
	s_waitcnt vmcnt(12)
	v_add_u32_e32 v2, v2, v5
	s_waitcnt vmcnt(11)
	v_add_u32_e32 v2, v2, v6
	s_waitcnt vmcnt(10)
	v_add_u32_e32 v2, v2, v7
	s_waitcnt vmcnt(9)
	v_add_u32_e32 v2, v2, v8
	s_waitcnt vmcnt(8)
	v_add_u32_e32 v2, v2, v9
	s_waitcnt vmcnt(7)
	v_add_u32_e32 v2, v2, v10
	s_waitcnt vmcnt(6)
	v_add_u32_e32 v2, v2, v11
	s_waitcnt vmcnt(5)
	v_add_u32_e32 v2, v2, v12
	s_waitcnt vmcnt(4)
	v_add_u32_e32 v2, v2, v13
	s_waitcnt vmcnt(3)
	v_add_u32_e32 v2, v2, v14
	s_waitcnt vmcnt(2)
	v_add_u32_e32 v2, v2, v15
	s_waitcnt vmcnt(1)
	v_add_u32_e32 v2, v2, v16
	s_waitcnt vmcnt(0)
	v_add_u32_e32 v2, v2, v17
	v_add_u32_e32 v2, 64, v2
	v_cmp_le_u32_e32 vcc, s33, v2
	s_cbranch_vccnz .LBB0_1766
	s_mov_b64 s[52:53], exec
	v_mbcnt_lo_u32_b32 v2, s52, 0
	v_mbcnt_hi_u32_b32 v2, s53, v2
	v_cmp_eq_u32_e32 vcc, 0, v2
	s_and_saveexec_b64 s[50:51], vcc
	s_cbranch_execz .LBB0_1765
	s_bcnt1_i32_b64 s0, s[52:53]
	s_lshl_b32 s0, s0, 3
	v_mov_b32_e32 v3, s0
	v_readlane_b32 s0, v242, 43
	v_readlane_b32 s1, v242, 44
	s_nop 4
	global_atomic_add v3, v1, v3, s[0:1] sc0

.LBB0_1966:
	v_mov_b32_e32 v31, -1
	s_mov_b64 s[42:43], exec
	v_readlane_b32 s0, v242, 26
	v_readlane_b32 s1, v242, 27
	s_and_b64 s[0:1], s[42:43], s[0:1]
	s_mov_b64 exec, s[0:1]
	s_cbranch_execz .LBB0_1971
	v_readlane_b32 s0, v242, 30
	v_readlane_b32 s1, v242, 31
	v_mov_b32_e32 v31, -1
	s_nop 3
	global_load_dword v2, v1, s[0:1] sc1
	v_readlane_b32 s0, v241, 2
	v_readlane_b32 s1, v241, 3
	s_nop 4
	global_load_dword v3, v1, s[0:1] sc1
	v_readlane_b32 s0, v241, 4
	v_readlane_b32 s1, v241, 5
	s_nop 4
	global_load_dword v4, v1, s[0:1] sc1
	v_readlane_b32 s0, v241, 6
	v_readlane_b32 s1, v241, 7
	s_nop 4
	global_load_dword v5, v1, s[0:1] sc1
	global_load_dword v6, v1, s[14:15] sc1
	global_load_dword v7, v1, s[16:17] sc1
	global_load_dword v8, v1, s[18:19] sc1
	global_load_dword v9, v1, s[20:21] sc1
	global_load_dword v10, v1, s[22:23] sc1
	global_load_dword v11, v1, s[24:25] sc1
	global_load_dword v12, v1, s[26:27] sc1
	global_load_dword v13, v1, s[28:29] sc1
	global_load_dword v14, v1, s[30:31] sc1
	global_load_dword v15, v1, s[34:35] sc1
	global_load_dword v16, v1, s[36:37] sc1
	global_load_dword v17, v1, s[38:39] sc1
	v_readlane_b32 s0, v242, 25
	s_mul_i32 s0, s84, s0
	s_waitcnt vmcnt(15)
	v_subrev_u32_e32 v2, s0, v2
	s_waitcnt vmcnt(14)
	v_add_u32_e32 v2, v2, v3
	s_waitcnt vmcnt(13)
	v_add_u32_e32 v2, v2, v4
	s_waitcnt vmcnt(12)
	v_add_u32_e32 v2, v2, v5
	s_waitcnt vmcnt(11)
	v_add_u32_e32 v2, v2, v6
	s_waitcnt vmcnt(10)
	v_add_u32_e32 v2, v2, v7
	s_waitcnt vmcnt(9)
	v_add_u32_e32 v2, v2, v8
	s_waitcnt vmcnt(8)
	v_add_u32_e32 v2, v2, v9
	s_waitcnt vmcnt(7)
	v_add_u32_e32 v2, v2, v10
	s_waitcnt vmcnt(6)
	v_add_u32_e32 v2, v2, v11
	s_waitcnt vmcnt(5)
	v_add_u32_e32 v2, v2, v12
	s_waitcnt vmcnt(4)
	v_add_u32_e32 v2, v2, v13
	s_waitcnt vmcnt(3)
	v_add_u32_e32 v2, v2, v14
	s_waitcnt vmcnt(2)
	v_add_u32_e32 v2, v2, v15
	s_waitcnt vmcnt(1)
	v_add_u32_e32 v2, v2, v16
	s_waitcnt vmcnt(0)
	v_add_u32_e32 v2, v2, v17
	v_add_u32_e32 v2, 64, v2
	v_cmp_le_u32_e32 vcc, s33, v2
	s_cbranch_vccnz .LBB0_1971
	s_mov_b64 s[50:51], exec
	v_mbcnt_lo_u32_b32 v2, s50, 0
	v_mbcnt_hi_u32_b32 v2, s51, v2
	v_cmp_eq_u32_e32 vcc, 0, v2
	s_and_saveexec_b64 s[48:49], vcc
	s_cbranch_execz .LBB0_1970
	s_bcnt1_i32_b64 s0, s[50:51]
	s_lshl_b32 s0, s0, 3
	v_mov_b32_e32 v3, s0
	v_readlane_b32 s0, v242, 43
	v_readlane_b32 s1, v242, 44
	s_nop 4
	global_atomic_add v3, v1, v3, s[0:1] sc0

.LBB0_2017:
	v_mov_b32_e32 v31, -1
	s_mov_b64 s[42:43], exec
	v_readlane_b32 s0, v242, 26
	v_readlane_b32 s1, v242, 27
	s_and_b64 s[0:1], s[42:43], s[0:1]
	s_mov_b64 exec, s[0:1]
	s_cbranch_execz .LBB0_2022
	v_readlane_b32 s0, v242, 30
	v_readlane_b32 s1, v242, 31
	v_mov_b32_e32 v31, -1
	s_nop 3
	global_load_dword v2, v1, s[0:1] sc1
	v_readlane_b32 s0, v241, 2
	v_readlane_b32 s1, v241, 3
	s_waitcnt vmcnt(0)
	v_subrev_u32_e32 v2, s41, v2
	s_nop 2
	global_load_dword v3, v1, s[0:1] sc1
	v_readlane_b32 s0, v241, 4
	v_readlane_b32 s1, v241, 5
	s_waitcnt vmcnt(0)
	v_add_u32_e32 v2, v2, v3
	s_nop 2
	global_load_dword v4, v1, s[0:1] sc1
	v_readlane_b32 s0, v241, 6
	v_readlane_b32 s1, v241, 7
	s_nop 4
	global_load_dword v5, v1, s[0:1] sc1
	global_load_dword v6, v1, s[14:15] sc1
	global_load_dword v7, v1, s[16:17] sc1
	global_load_dword v8, v1, s[18:19] sc1
	global_load_dword v9, v1, s[20:21] sc1
	global_load_dword v10, v1, s[22:23] sc1
	global_load_dword v11, v1, s[24:25] sc1
	global_load_dword v12, v1, s[26:27] sc1
	global_load_dword v13, v1, s[28:29] sc1
	global_load_dword v14, v1, s[30:31] sc1
	global_load_dword v15, v1, s[34:35] sc1
	global_load_dword v16, v1, s[36:37] sc1
	global_load_dword v17, v1, s[38:39] sc1
	s_movk_i32 s0, 0x7f
	s_waitcnt vmcnt(13)
	v_add_u32_e32 v2, v2, v4
	s_waitcnt vmcnt(12)
	v_add_u32_e32 v2, v2, v5
	s_waitcnt vmcnt(11)
	v_add_u32_e32 v2, v2, v6
	s_waitcnt vmcnt(10)
	v_add_u32_e32 v2, v2, v7
	s_waitcnt vmcnt(9)
	v_add_u32_e32 v2, v2, v8
	s_waitcnt vmcnt(8)
	v_add_u32_e32 v2, v2, v9
	s_waitcnt vmcnt(7)
	v_add_u32_e32 v2, v2, v10
	s_waitcnt vmcnt(6)
	v_add_u32_e32 v2, v2, v11
	s_waitcnt vmcnt(5)
	v_add_u32_e32 v2, v2, v12
	s_waitcnt vmcnt(4)
	v_add_u32_e32 v2, v2, v13
	s_waitcnt vmcnt(3)
	v_add_u32_e32 v2, v2, v14
	s_waitcnt vmcnt(2)
	v_add_u32_e32 v2, v2, v15
	s_waitcnt vmcnt(1)
	v_add_u32_e32 v2, v2, v16
	s_waitcnt vmcnt(0)
	v_add_u32_e32 v2, v2, v17
	v_cmp_lt_u32_e32 vcc, s0, v2
	s_cbranch_vccnz .LBB0_2022
	s_mov_b64 s[50:51], exec
	v_mbcnt_lo_u32_b32 v2, s50, 0
	v_mbcnt_hi_u32_b32 v2, s51, v2
	v_cmp_eq_u32_e32 vcc, 0, v2
	s_and_saveexec_b64 s[48:49], vcc
	s_cbranch_execz .LBB0_2021
	s_bcnt1_i32_b64 s0, s[50:51]
	s_lshl_b32 s0, s0, 3
	v_mov_b32_e32 v3, s0
	v_readlane_b32 s0, v242, 43
	v_readlane_b32 s1, v242, 44
	s_nop 4
	global_atomic_add v3, v1, v3, s[0:1] sc0
